# MLA loop restructured: waves 0-3 / 4-7 one segment apart (matrix segment beside softmax segment on every SIMD), two barriers per tile
# speedup vs baseline: 1.0090x; 1.0047x over previous
.LBB0_561:
	s_waitcnt lgkmcnt(0)
	s_barrier
	s_cmp_ge_u32 s3, 4
	s_cselect_b32 s96, 1, 0
	s_cbranch_scc0 .Lm2_a_noidle
	s_barrier
	s_cmp_gt_u32 s58, s19
	s_cbranch_scc1 .Lm2_iss_end_ad
	s_cmp_eq_u32 s58, 2
	s_cbranch_scc1 .Lm2_iss_nov_ad
	s_mov_b32 m0, s54
	v_lshl_add_u64 v[254:255], v[164:165], 1, s[100:101]
	global_load_lds_dwordx4 v[254:255], off
	s_mov_b32 m0, s55
	v_lshl_add_u64 v[254:255], v[166:167], 1, s[100:101]
	global_load_lds_dwordx4 v[254:255], off
.Lm2_iss_nov_ad:
	s_cmp_eq_u32 s58, s19
	s_cbranch_scc1 .Lm2_iss_end_ad
	s_cmp_lt_u32 s58, s18
	s_cselect_b32 s0, 0, s18
	s_cselect_b32 s1, s6, s13
	s_lshl_b32 s0, s0, 6
	s_sub_i32 s0, s1, s0
	s_add_i32 s0, s51, s0
	s_ashr_i32 s1, s0, 31
	s_lshl_b64 s[10:11], s[0:1], 12
	s_add_u32 s16, s20, s10
	s_addc_u32 s17, s21, s11
	s_mov_b32 m0, s23
	v_lshl_add_u64 v[254:255], v[160:161], 1, s[16:17]
	global_load_lds_dwordx4 v[254:255], off
	s_mov_b32 m0, s7
	v_lshl_add_u64 v[254:255], v[162:163], 1, s[16:17]
	global_load_lds_dwordx4 v[254:255], off
	s_mov_b32 m0, s30
	v_mad_i64_i32 v[254:255], s[0:1], s0, v180, v[168:169]
	global_load_lds_dwordx4 v[254:255], off
	s_add_u32 s100, s16, 0x100
	s_addc_u32 s101, s17, 0
.Lm2_iss_end_ad:
.Lm2_a_noidle:
	v_add_f32_e32 v212, 0, v150
	v_add_f32_e32 v212, v152, v212
	v_add_f32_e32 v212, v145, v212
	v_add_f32_e32 v212, v151, v212
	v_add_f32_e32 v212, v146, v212
	v_add_f32_e32 v212, v149, v212
	v_add_f32_e32 v212, v147, v212
	v_add_f32_e32 v212, v148, v212
	v_add_f32_e32 v212, v93, v212
	v_add_f32_e32 v212, v95, v212
	v_add_f32_e32 v212, v91, v212
	v_add_f32_e32 v212, v94, v212
	v_add_f32_e32 v212, v89, v212
	v_add_f32_e32 v212, v92, v212
	v_add_f32_e32 v212, v88, v212
	v_add_f32_e32 v212, v90, v212
	v_cvt_pk_bf16_f32 v144, v150, v152
	v_cvt_pk_bf16_f32 v145, v145, v151
	v_cvt_pk_bf16_f32 v146, v146, v149
	v_cvt_pk_bf16_f32 v147, v147, v148
	v_cvt_pk_bf16_f32 v148, v93, v95
	v_cvt_pk_bf16_f32 v149, v91, v94
	v_cvt_pk_bf16_f32 v150, v89, v92
	v_cvt_pk_bf16_f32 v151, v88, v90
	v_mov_b32_e32 v72, v70
	v_mov_b32_e32 v73, v71
	v_mov_b32_e32 v74, v68
	v_mov_b32_e32 v75, v69
	v_mov_b32_e32 v76, v66
	v_mov_b32_e32 v77, v67
	v_mov_b32_e32 v78, v64
	v_mov_b32_e32 v79, v65
	v_mov_b32_e32 v64, v86
	v_mov_b32_e32 v65, v87
	v_mov_b32_e32 v66, v84
	v_mov_b32_e32 v67, v85
	v_mov_b32_e32 v68, v82
	v_mov_b32_e32 v69, v83
	v_mov_b32_e32 v70, v80
	v_mov_b32_e32 v71, v81
	v_permlane32_swap_b32_e32 v144, v146
	v_permlane32_swap_b32_e32 v145, v147
	v_permlane32_swap_b32_e32 v148, v150
	v_permlane32_swap_b32_e32 v149, v151
	v_exp_f32_e32 v64, v64
	v_exp_f32_e32 v65, v65
	v_add_f32_e32 v212, v64, v212
	v_exp_f32_e32 v66, v66
	v_add_f32_e32 v212, v65, v212
	v_exp_f32_e32 v67, v67
	v_add_f32_e32 v212, v66, v212
	v_exp_f32_e32 v68, v68
	v_add_f32_e32 v212, v67, v212
	v_exp_f32_e32 v69, v69
	v_add_f32_e32 v212, v68, v212
	v_exp_f32_e32 v70, v70
	v_add_f32_e32 v212, v69, v212
	v_exp_f32_e32 v71, v71
	v_add_f32_e32 v212, v70, v212
	v_exp_f32_e32 v72, v72
	v_add_f32_e32 v212, v71, v212
	v_exp_f32_e32 v73, v73
	v_add_f32_e32 v212, v72, v212
	v_exp_f32_e32 v74, v74
	v_add_f32_e32 v212, v73, v212
	v_exp_f32_e32 v75, v75
	v_add_f32_e32 v212, v74, v212
	v_exp_f32_e32 v76, v76
	v_add_f32_e32 v212, v75, v212
	v_exp_f32_e32 v77, v77
	v_add_f32_e32 v212, v76, v212
	v_exp_f32_e32 v78, v78
	v_add_f32_e32 v212, v77, v212
	v_exp_f32_e32 v79, v79
	v_add_f32_e32 v212, v78, v212
	v_mov_b32_e32 v213, v212
	v_add_f32_e32 v212, v79, v212
	v_mov_b32_e32 v213, v212
	v_cvt_pk_bf16_f32 v152, v64, v65
	v_cvt_pk_bf16_f32 v153, v66, v67
	v_cvt_pk_bf16_f32 v154, v68, v69
	v_cvt_pk_bf16_f32 v155, v70, v71
	v_cvt_pk_bf16_f32 v156, v72, v73
	v_cvt_pk_bf16_f32 v157, v74, v75
	v_cvt_pk_bf16_f32 v158, v76, v77
	v_cvt_pk_bf16_f32 v159, v78, v79
	v_permlane32_swap_b32_e32 v212, v213
	v_add_f32_e32 v252, v212, v213
	v_fma_f32 v183, v207, v183, v252
	v_permlane32_swap_b32_e32 v152, v154
	v_permlane32_swap_b32_e32 v153, v155
	v_permlane32_swap_b32_e32 v156, v158
	v_permlane32_swap_b32_e32 v157, v159
	s_waitcnt lgkmcnt(0)
	s_barrier
.Lmla_loop:
	ds_read_b128 v[214:217], v193 offset:57344
	ds_read_b128 v[218:221], v186 offset:57344
	ds_read_b128 v[222:225], v187 offset:57344
	ds_read_b128 v[226:229], v188 offset:57344
	ds_read_b128 v[230:233], v189 offset:57344
	ds_read_b128 v[234:237], v190 offset:57344
	ds_read_b128 v[238:241], v191 offset:57344
	ds_read_b128 v[242:245], v192 offset:57344
	s_cmp_eq_u32 s96, 0
	s_cbranch_scc0 .Lm2_cskip_o
	s_cmp_gt_u32 s58, s19
	s_cbranch_scc1 .Lm2_iss_end_co
	s_cmp_eq_u32 s58, 2
	s_cbranch_scc1 .Lm2_iss_nov_co
	s_mov_b32 m0, s54
	v_lshl_add_u64 v[254:255], v[164:165], 1, s[100:101]
	global_load_lds_dwordx4 v[254:255], off
	s_mov_b32 m0, s55
	v_lshl_add_u64 v[254:255], v[166:167], 1, s[100:101]
	global_load_lds_dwordx4 v[254:255], off

.Lm2_iss_end_co:
.Lm2_cskip_o:
	s_waitcnt lgkmcnt(7)
	v_mfma_f32_32x32x16_bf16 v[80:95], v[214:217], v[124:127], 0
	v_add_u32_e32 v211, 0x6000, v203
	ds_read_b128 v[214:217], v211 offset:49152
	s_waitcnt lgkmcnt(7)
	v_mfma_f32_32x32x16_bf16 v[80:95], v[218:221], v[120:123], v[80:95]
	v_add_u32_e32 v211, 0x6000, v204
	ds_read_b128 v[218:221], v211 offset:49152
	s_waitcnt lgkmcnt(7)
	v_mfma_f32_32x32x16_bf16 v[80:95], v[222:225], v[116:119], v[80:95]
	v_add_u32_e32 v211, 0x6000, v205
	ds_read_b128 v[222:225], v211 offset:49152
	s_waitcnt lgkmcnt(7)
	v_mfma_f32_32x32x16_bf16 v[80:95], v[226:229], v[112:115], v[80:95]
	v_add_u32_e32 v211, 0x6000, v206
	ds_read_b128 v[226:229], v211 offset:49152
	s_waitcnt lgkmcnt(7)
	v_mfma_f32_32x32x16_bf16 v[80:95], v[230:233], v[108:111], v[80:95]
	v_add_u32_e32 v211, v209, v194
	ds_read_b128 v[230:233], v211 offset:8192
	s_waitcnt lgkmcnt(7)
	v_mfma_f32_32x32x16_bf16 v[80:95], v[234:237], v[104:107], v[80:95]
	v_add_u32_e32 v211, v209, v195
	ds_read_b128 v[234:237], v211 offset:8192
	s_waitcnt lgkmcnt(7)
	v_mfma_f32_32x32x16_bf16 v[80:95], v[238:241], v[100:103], v[80:95]
	v_add_u32_e32 v211, v209, v196
	ds_read_b128 v[238:241], v211 offset:8192
	s_waitcnt lgkmcnt(7)
	v_mfma_f32_32x32x16_bf16 v[80:95], v[242:245], v[96:99], v[80:95]
	v_add_u32_e32 v211, v209, v197
	ds_read_b128 v[242:245], v211 offset:8192
	s_waitcnt lgkmcnt(7)
	v_mfma_f32_32x32x16_bf16 v[80:95], v[214:217], v[128:131], v[80:95]
	v_add_u32_e32 v211, v209, v198
	ds_read_b128 v[214:217], v211 offset:8192
	s_waitcnt lgkmcnt(7)
	v_mfma_f32_32x32x16_bf16 v[80:95], v[218:221], v[132:135], v[80:95]
	v_add_u32_e32 v211, v209, v199
	ds_read_b128 v[218:221], v211 offset:8192
	s_waitcnt lgkmcnt(7)
	v_mfma_f32_32x32x16_bf16 v[80:95], v[222:225], v[136:139], v[80:95]
	v_add_u32_e32 v211, v209, v200
	ds_read_b128 v[222:225], v211 offset:8192
	s_waitcnt lgkmcnt(7)
	v_mfma_f32_32x32x16_bf16 v[80:95], v[226:229], v[140:143], v[80:95]
	v_add_u32_e32 v211, v209, v201
	ds_read_b128 v[226:229], v211 offset:8192
	s_waitcnt lgkmcnt(7)
	v_mfma_f32_32x32x16_bf16 v[64:79], v[230:233], v[124:127], 0
	v_add_u32_e32 v211, 0x6000, v203
	ds_read_b128 v[230:233], v211 offset:53248
	s_waitcnt lgkmcnt(7)
	v_mfma_f32_32x32x16_bf16 v[64:79], v[234:237], v[120:123], v[64:79]
	v_add_u32_e32 v211, 0x6000, v204
	ds_read_b128 v[234:237], v211 offset:53248
	s_waitcnt lgkmcnt(7)
	v_mfma_f32_32x32x16_bf16 v[64:79], v[238:241], v[116:119], v[64:79]
	v_add_u32_e32 v211, 0x6000, v205
	ds_read_b128 v[238:241], v211 offset:53248
	s_waitcnt lgkmcnt(7)
	v_mfma_f32_32x32x16_bf16 v[64:79], v[242:245], v[112:115], v[64:79]
	v_add_u32_e32 v211, 0x6000, v206
	ds_read_b128 v[242:245], v211 offset:53248
	s_waitcnt lgkmcnt(7)
	v_mfma_f32_32x32x16_bf16 v[64:79], v[214:217], v[108:111], v[64:79]
	s_waitcnt lgkmcnt(6)
	v_mfma_f32_32x32x16_bf16 v[64:79], v[218:221], v[104:107], v[64:79]
	s_waitcnt lgkmcnt(5)
	v_mfma_f32_32x32x16_bf16 v[64:79], v[222:225], v[100:103], v[64:79]
	ds_read_b64_tr_b16 v[214:215], v185
	ds_read_b64_tr_b16 v[216:217], v185 offset:2048
	s_waitcnt lgkmcnt(6)
	v_mfma_f32_32x32x16_bf16 v[64:79], v[226:229], v[96:99], v[64:79]
	ds_read_b64_tr_b16 v[218:219], v185 offset:4096
	ds_read_b64_tr_b16 v[220:221], v185 offset:6144
	s_waitcnt lgkmcnt(7)
	v_mfma_f32_32x32x16_bf16 v[64:79], v[230:233], v[128:131], v[64:79]
	ds_read_b64_tr_b16 v[222:223], v185 offset:8192
	ds_read_b64_tr_b16 v[224:225], v185 offset:10240
	s_waitcnt lgkmcnt(8)
	v_mfma_f32_32x32x16_bf16 v[64:79], v[234:237], v[132:135], v[64:79]
	ds_read_b64_tr_b16 v[226:227], v185 offset:12288
	ds_read_b64_tr_b16 v[228:229], v185 offset:14336
	s_waitcnt lgkmcnt(9)
	v_mfma_f32_32x32x16_bf16 v[64:79], v[238:241], v[136:139], v[64:79]
	ds_read_b64_tr_b16 v[230:231], v185 offset:512
	ds_read_b64_tr_b16 v[232:233], v185 offset:2560
	s_waitcnt lgkmcnt(10)
	v_mfma_f32_32x32x16_bf16 v[64:79], v[242:245], v[140:143], v[64:79]
	ds_read_b64_tr_b16 v[234:235], v185 offset:4608
	ds_read_b64_tr_b16 v[236:237], v185 offset:6656
	s_waitcnt lgkmcnt(10)
	v_mfma_f32_32x32x16_bf16 v[0:15], v[144:147], v[214:217], v[0:15]
	ds_read_b64_tr_b16 v[238:239], v185 offset:8704
	ds_read_b64_tr_b16 v[240:241], v185 offset:10752
	s_waitcnt lgkmcnt(10)
	v_mfma_f32_32x32x16_bf16 v[0:15], v[148:151], v[218:221], v[0:15]
	ds_read_b64_tr_b16 v[242:243], v185 offset:12800
	ds_read_b64_tr_b16 v[244:245], v185 offset:14848
	s_waitcnt lgkmcnt(10)
	v_mfma_f32_32x32x16_bf16 v[0:15], v[152:155], v[222:225], v[0:15]
	ds_read_b64_tr_b16 v[214:215], v185 offset:1024
	ds_read_b64_tr_b16 v[216:217], v185 offset:3072
	s_waitcnt lgkmcnt(10)
	v_mfma_f32_32x32x16_bf16 v[0:15], v[156:159], v[226:229], v[0:15]
	ds_read_b64_tr_b16 v[218:219], v185 offset:5120
	ds_read_b64_tr_b16 v[220:221], v185 offset:7168
	s_waitcnt lgkmcnt(10)
	v_mfma_f32_32x32x16_bf16 v[48:63], v[144:147], v[230:233], v[48:63]
	ds_read_b64_tr_b16 v[222:223], v185 offset:9216
	ds_read_b64_tr_b16 v[224:225], v185 offset:11264
	s_waitcnt lgkmcnt(10)
	v_mfma_f32_32x32x16_bf16 v[48:63], v[148:151], v[234:237], v[48:63]
	ds_read_b64_tr_b16 v[226:227], v185 offset:13312
	ds_read_b64_tr_b16 v[228:229], v185 offset:15360
	s_waitcnt lgkmcnt(10)
	v_mfma_f32_32x32x16_bf16 v[48:63], v[152:155], v[238:241], v[48:63]
	ds_read_b64_tr_b16 v[230:231], v185 offset:1536
	ds_read_b64_tr_b16 v[232:233], v185 offset:3584
	s_waitcnt lgkmcnt(10)
	v_mfma_f32_32x32x16_bf16 v[48:63], v[156:159], v[242:245], v[48:63]
	ds_read_b64_tr_b16 v[234:235], v185 offset:5632
	ds_read_b64_tr_b16 v[236:237], v185 offset:7680
	s_waitcnt lgkmcnt(10)
	v_mfma_f32_32x32x16_bf16 v[32:47], v[144:147], v[214:217], v[32:47]
	ds_read_b64_tr_b16 v[238:239], v185 offset:9728
	ds_read_b64_tr_b16 v[240:241], v185 offset:11776
	s_waitcnt lgkmcnt(10)
	v_mfma_f32_32x32x16_bf16 v[32:47], v[148:151], v[218:221], v[32:47]
	ds_read_b64_tr_b16 v[242:243], v185 offset:13824
	ds_read_b64_tr_b16 v[244:245], v185 offset:15872
	s_waitcnt lgkmcnt(10)
	v_mfma_f32_32x32x16_bf16 v[32:47], v[152:155], v[222:225], v[32:47]
	s_waitcnt lgkmcnt(8)
	v_mfma_f32_32x32x16_bf16 v[32:47], v[156:159], v[226:229], v[32:47]
	s_waitcnt lgkmcnt(6)
	v_mfma_f32_32x32x16_bf16 v[16:31], v[144:147], v[230:233], v[16:31]
	s_waitcnt lgkmcnt(4)
	v_mfma_f32_32x32x16_bf16 v[16:31], v[148:151], v[234:237], v[16:31]
	s_waitcnt lgkmcnt(2)
	v_mfma_f32_32x32x16_bf16 v[16:31], v[152:155], v[238:241], v[16:31]
	s_waitcnt lgkmcnt(0)
	v_mfma_f32_32x32x16_bf16 v[16:31], v[156:159], v[242:245], v[16:31]
	s_add_i32 s58, s58, 1
	s_cmp_eq_u32 s96, 1
	s_cbranch_scc0 .Lm2_cw_o
	s_waitcnt vmcnt(0)
.Lm2_cw_o:
	s_waitcnt lgkmcnt(0)
	s_barrier
	s_cmp_eq_u32 s96, 1
	s_cbranch_scc0 .Lm2_lskip_o
	s_cmp_gt_u32 s58, s19
	s_cbranch_scc1 .Lm2_iss_end_lo
	s_cmp_eq_u32 s58, 2
	s_cbranch_scc1 .Lm2_iss_nov_lo
	s_mov_b32 m0, s22
	v_lshl_add_u64 v[254:255], v[164:165], 1, s[100:101]
	global_load_lds_dwordx4 v[254:255], off
	s_mov_b32 m0, s31
	v_lshl_add_u64 v[254:255], v[166:167], 1, s[100:101]
	global_load_lds_dwordx4 v[254:255], off
.Lm2_iss_nov_lo:
	s_cmp_eq_u32 s58, s19
	s_cbranch_scc1 .Lm2_iss_end_lo
	s_cmp_lt_u32 s58, s18
	s_cselect_b32 s0, 0, s18
	s_cselect_b32 s1, s6, s13
	s_lshl_b32 s0, s0, 6
	s_sub_i32 s0, s1, s0
	s_add_i32 s0, s51, s0
	s_add_i32 s0, s0, 64
	s_ashr_i32 s1, s0, 31
	s_lshl_b64 s[10:11], s[0:1], 12
	s_add_u32 s16, s20, s10
	s_addc_u32 s17, s21, s11
	s_mov_b32 m0, s44
	v_lshl_add_u64 v[254:255], v[160:161], 1, s[16:17]
	global_load_lds_dwordx4 v[254:255], off
	s_mov_b32 m0, s45
	v_lshl_add_u64 v[254:255], v[162:163], 1, s[16:17]
	global_load_lds_dwordx4 v[254:255], off
	s_mov_b32 m0, s49
	v_mad_i64_i32 v[254:255], s[0:1], s0, v180, v[168:169]
	global_load_lds_dwordx4 v[254:255], off
	s_add_u32 s100, s16, 0x100
	s_addc_u32 s101, s17, 0
.Lm2_iss_end_lo:
.Lm2_lskip_o:
	v_max_f32_e32 v249, v80, v81
	v_max3_f32 v249, v249, v82, v83
	v_max3_f32 v249, v249, v84, v85
	v_max3_f32 v249, v249, v86, v87
	v_max3_f32 v249, v249, v88, v89
	v_max3_f32 v249, v249, v90, v91
	v_max3_f32 v249, v249, v92, v93
	v_max3_f32 v249, v249, v94, v95
	v_max3_f32 v249, v249, v64, v65
	v_max3_f32 v249, v249, v66, v67
	v_max3_f32 v249, v249, v68, v69
	v_max3_f32 v249, v249, v70, v71
	v_max3_f32 v249, v249, v72, v73
	v_max3_f32 v249, v249, v74, v75
	v_max3_f32 v249, v249, v76, v77
	v_max3_f32 v249, v249, v78, v79
	v_mov_b32_e32 v250, v249
	s_nop 1
	v_permlane32_swap_b32_e32 v249, v250
	v_max_f32_e32 v249, v249, v250
	v_sub_f32_e32 v250, v249, v208
	v_cmp_ge_f32_e32 vcc, s40, v250
	v_max_f32_e32 v249, v208, v249
	v_sub_f32_e32 v250, v208, v249
	v_mul_f32_e32 v250, 0x3dd53b94, v250
	v_exp_f32_e32 v250, v250
	s_cmp_eq_u64 vcc, exec
	s_cselect_b64 s[10:11], -1, 0
	v_cndmask_b32_e64 v207, v250, 1.0, s[10:11]
	v_cndmask_b32_e64 v208, v249, v208, s[10:11]
	v_mul_f32_e32 v251, 0xbdd53b94, v208
	v_fmamk_f32 v80, v80, 0x3dd53b94, v251
	v_fmamk_f32 v81, v81, 0x3dd53b94, v251
	v_fmamk_f32 v82, v82, 0x3dd53b94, v251
	v_fmamk_f32 v83, v83, 0x3dd53b94, v251
	v_fmamk_f32 v84, v84, 0x3dd53b94, v251
	v_fmamk_f32 v85, v85, 0x3dd53b94, v251
	v_fmamk_f32 v86, v86, 0x3dd53b94, v251
	v_fmamk_f32 v87, v87, 0x3dd53b94, v251
	v_fmamk_f32 v88, v88, 0x3dd53b94, v251
	v_fmamk_f32 v89, v89, 0x3dd53b94, v251
	v_fmamk_f32 v90, v90, 0x3dd53b94, v251
	v_fmamk_f32 v91, v91, 0x3dd53b94, v251
	v_fmamk_f32 v92, v92, 0x3dd53b94, v251
	v_fmamk_f32 v93, v93, 0x3dd53b94, v251
	v_fmamk_f32 v94, v94, 0x3dd53b94, v251
	v_fmamk_f32 v95, v95, 0x3dd53b94, v251
	v_fmamk_f32 v64, v64, 0x3dd53b94, v251
	v_fmamk_f32 v65, v65, 0x3dd53b94, v251
	v_fmamk_f32 v66, v66, 0x3dd53b94, v251
	v_fmamk_f32 v67, v67, 0x3dd53b94, v251
	v_fmamk_f32 v68, v68, 0x3dd53b94, v251
	v_fmamk_f32 v69, v69, 0x3dd53b94, v251
	v_fmamk_f32 v70, v70, 0x3dd53b94, v251
	v_fmamk_f32 v71, v71, 0x3dd53b94, v251
	v_fmamk_f32 v72, v72, 0x3dd53b94, v251
	v_fmamk_f32 v73, v73, 0x3dd53b94, v251
	v_fmamk_f32 v74, v74, 0x3dd53b94, v251
	v_fmamk_f32 v75, v75, 0x3dd53b94, v251
	v_fmamk_f32 v76, v76, 0x3dd53b94, v251
	v_fmamk_f32 v77, v77, 0x3dd53b94, v251
	v_fmamk_f32 v78, v78, 0x3dd53b94, v251
	v_fmamk_f32 v79, v79, 0x3dd53b94, v251
	v_exp_f32_e32 v80, v80
	v_exp_f32_e32 v81, v81
	v_add_f32_e32 v212, 0, v80
	v_exp_f32_e32 v82, v82
	v_add_f32_e32 v212, v81, v212
	v_exp_f32_e32 v83, v83
	v_add_f32_e32 v212, v82, v212
	v_exp_f32_e32 v84, v84
	v_add_f32_e32 v212, v83, v212
	v_exp_f32_e32 v85, v85
	v_add_f32_e32 v212, v84, v212
	v_exp_f32_e32 v86, v86
	v_add_f32_e32 v212, v85, v212
	v_exp_f32_e32 v87, v87
	v_add_f32_e32 v212, v86, v212
	v_exp_f32_e32 v88, v88
	v_add_f32_e32 v212, v87, v212
	v_exp_f32_e32 v89, v89
	v_add_f32_e32 v212, v88, v212
	v_exp_f32_e32 v90, v90
	v_add_f32_e32 v212, v89, v212
	v_exp_f32_e32 v91, v91
	v_add_f32_e32 v212, v90, v212
	v_exp_f32_e32 v92, v92
	v_add_f32_e32 v212, v91, v212
	v_exp_f32_e32 v93, v93
	v_add_f32_e32 v212, v92, v212
	v_exp_f32_e32 v94, v94
	v_add_f32_e32 v212, v93, v212
	v_exp_f32_e32 v95, v95
	v_add_f32_e32 v212, v94, v212
	v_exp_f32_e32 v64, v64
	v_add_f32_e32 v212, v95, v212
	v_exp_f32_e32 v65, v65
	v_add_f32_e32 v212, v64, v212
	v_exp_f32_e32 v66, v66
	v_add_f32_e32 v212, v65, v212
	v_exp_f32_e32 v67, v67
	v_add_f32_e32 v212, v66, v212
	v_exp_f32_e32 v68, v68
	v_add_f32_e32 v212, v67, v212
	v_exp_f32_e32 v69, v69
	v_add_f32_e32 v212, v68, v212
	v_exp_f32_e32 v70, v70
	v_add_f32_e32 v212, v69, v212
	v_exp_f32_e32 v71, v71
	v_add_f32_e32 v212, v70, v212
	v_exp_f32_e32 v72, v72
	v_add_f32_e32 v212, v71, v212
	v_exp_f32_e32 v73, v73
	v_add_f32_e32 v212, v72, v212
	v_exp_f32_e32 v74, v74
	v_add_f32_e32 v212, v73, v212
	v_exp_f32_e32 v75, v75
	v_add_f32_e32 v212, v74, v212
	v_exp_f32_e32 v76, v76
	v_add_f32_e32 v212, v75, v212
	v_exp_f32_e32 v77, v77
	v_add_f32_e32 v212, v76, v212
	v_exp_f32_e32 v78, v78
	v_add_f32_e32 v212, v77, v212
	v_exp_f32_e32 v79, v79
	v_add_f32_e32 v212, v78, v212
	v_mov_b32_e32 v213, v212
	v_add_f32_e32 v212, v79, v212
	v_mov_b32_e32 v213, v212
	v_cvt_pk_bf16_f32 v144, v80, v81
	v_cvt_pk_bf16_f32 v145, v82, v83
	v_cvt_pk_bf16_f32 v146, v84, v85
	v_cvt_pk_bf16_f32 v147, v86, v87
	v_cvt_pk_bf16_f32 v148, v88, v89
	v_cvt_pk_bf16_f32 v149, v90, v91
	v_cvt_pk_bf16_f32 v150, v92, v93
	v_cvt_pk_bf16_f32 v151, v94, v95
	v_cvt_pk_bf16_f32 v152, v64, v65
	v_cvt_pk_bf16_f32 v153, v66, v67
	v_cvt_pk_bf16_f32 v154, v68, v69
	v_cvt_pk_bf16_f32 v155, v70, v71
	v_cvt_pk_bf16_f32 v156, v72, v73
	v_cvt_pk_bf16_f32 v157, v74, v75
	v_cvt_pk_bf16_f32 v158, v76, v77
	v_cvt_pk_bf16_f32 v159, v78, v79
	v_permlane32_swap_b32_e32 v212, v213
	v_add_f32_e32 v252, v212, v213
	v_fma_f32 v183, v207, v183, v252
	v_permlane32_swap_b32_e32 v144, v146
	v_permlane32_swap_b32_e32 v145, v147
	v_permlane32_swap_b32_e32 v148, v150
	v_permlane32_swap_b32_e32 v149, v151
	v_permlane32_swap_b32_e32 v152, v154
	v_permlane32_swap_b32_e32 v153, v155
	v_permlane32_swap_b32_e32 v156, v158
	v_permlane32_swap_b32_e32 v157, v159
	v_cmp_gt_f32_e32 vcc, 1.0, v207
	s_cbranch_vccz .Lmla_noresc_m2o
	s_and_saveexec_b64 s[0:1], s[8:9]
	ds_write_b32 v182, v207 offset:128
	s_or_b64 exec, exec, s[0:1]
	s_waitcnt lgkmcnt(0)
	v_add_u32_e32 v253, s50, v181
	ds_read_b128 v[92:95], v253 offset:224
	ds_read_b128 v[88:91], v253 offset:192
	ds_read_b128 v[84:87], v253 offset:160
	ds_read_b128 v[80:83], v253 offset:128
	s_waitcnt lgkmcnt(3)
	v_pk_mul_f32 v[12:13], v[12:13], v[92:93]
	v_pk_mul_f32 v[14:15], v[14:15], v[94:95]
	v_pk_mul_f32 v[60:61], v[60:61], v[92:93]
	v_pk_mul_f32 v[62:63], v[62:63], v[94:95]
	v_pk_mul_f32 v[44:45], v[44:45], v[92:93]
	v_pk_mul_f32 v[46:47], v[46:47], v[94:95]
	v_pk_mul_f32 v[28:29], v[28:29], v[92:93]
	v_pk_mul_f32 v[30:31], v[30:31], v[94:95]
	s_waitcnt lgkmcnt(2)
	v_pk_mul_f32 v[8:9], v[8:9], v[88:89]
	v_pk_mul_f32 v[10:11], v[10:11], v[90:91]
	v_pk_mul_f32 v[56:57], v[56:57], v[88:89]
	v_pk_mul_f32 v[58:59], v[58:59], v[90:91]
	v_pk_mul_f32 v[40:41], v[40:41], v[88:89]
	v_pk_mul_f32 v[42:43], v[42:43], v[90:91]
	v_pk_mul_f32 v[24:25], v[24:25], v[88:89]
	v_pk_mul_f32 v[26:27], v[26:27], v[90:91]
	s_waitcnt lgkmcnt(1)
	v_pk_mul_f32 v[4:5], v[4:5], v[84:85]
	v_pk_mul_f32 v[6:7], v[6:7], v[86:87]
	v_pk_mul_f32 v[52:53], v[52:53], v[84:85]
	v_pk_mul_f32 v[54:55], v[54:55], v[86:87]
	v_pk_mul_f32 v[36:37], v[36:37], v[84:85]
	v_pk_mul_f32 v[38:39], v[38:39], v[86:87]
	v_pk_mul_f32 v[20:21], v[20:21], v[84:85]
	v_pk_mul_f32 v[22:23], v[22:23], v[86:87]
	s_waitcnt lgkmcnt(0)
	v_pk_mul_f32 v[0:1], v[0:1], v[80:81]
	v_pk_mul_f32 v[2:3], v[2:3], v[82:83]
	v_pk_mul_f32 v[48:49], v[48:49], v[80:81]
	v_pk_mul_f32 v[50:51], v[50:51], v[82:83]
	v_pk_mul_f32 v[32:33], v[32:33], v[80:81]
	v_pk_mul_f32 v[34:35], v[34:35], v[82:83]
	v_pk_mul_f32 v[16:17], v[16:17], v[80:81]
	v_pk_mul_f32 v[18:19], v[18:19], v[82:83]
.Lmla_noresc_m2o:
	s_cmp_eq_u32 s96, 0
	s_cbranch_scc0 .Lm2_lw_o
	s_waitcnt vmcnt(0)
.Lm2_lw_o:
	s_waitcnt lgkmcnt(0)
	s_barrier
	ds_read_b128 v[214:217], v193 offset:32768
	ds_read_b128 v[218:221], v186 offset:32768
	ds_read_b128 v[222:225], v187 offset:32768
	ds_read_b128 v[226:229], v188 offset:32768
	ds_read_b128 v[230:233], v189 offset:32768
	ds_read_b128 v[234:237], v190 offset:32768
	ds_read_b128 v[238:241], v191 offset:32768
	ds_read_b128 v[242:245], v192 offset:32768
	s_cmp_eq_u32 s96, 0
	s_cbranch_scc0 .Lm2_cskip_e
	s_cmp_gt_u32 s58, s19
	s_cbranch_scc1 .Lm2_iss_end_ce
	s_cmp_eq_u32 s58, 2
	s_cbranch_scc1 .Lm2_iss_nov_ce
	s_mov_b32 m0, s22
	v_lshl_add_u64 v[254:255], v[164:165], 1, s[100:101]
	global_load_lds_dwordx4 v[254:255], off
	s_mov_b32 m0, s31
	v_lshl_add_u64 v[254:255], v[166:167], 1, s[100:101]
	global_load_lds_dwordx4 v[254:255], off

.Lm2_iss_end_ce:
.Lm2_cskip_e:
	s_waitcnt lgkmcnt(7)
	v_mfma_f32_32x32x16_bf16 v[80:95], v[214:217], v[124:127], 0
	ds_read_b128 v[214:217], v203 offset:49152
	s_waitcnt lgkmcnt(7)
	v_mfma_f32_32x32x16_bf16 v[80:95], v[218:221], v[120:123], v[80:95]
	ds_read_b128 v[218:221], v204 offset:49152
	s_waitcnt lgkmcnt(7)
	v_mfma_f32_32x32x16_bf16 v[80:95], v[222:225], v[116:119], v[80:95]
	ds_read_b128 v[222:225], v205 offset:49152
	s_waitcnt lgkmcnt(7)
	v_mfma_f32_32x32x16_bf16 v[80:95], v[226:229], v[112:115], v[80:95]
	ds_read_b128 v[226:229], v206 offset:49152
	s_waitcnt lgkmcnt(7)
	v_mfma_f32_32x32x16_bf16 v[80:95], v[230:233], v[108:111], v[80:95]
	ds_read_b128 v[230:233], v193 offset:40960
	s_waitcnt lgkmcnt(7)
	v_mfma_f32_32x32x16_bf16 v[80:95], v[234:237], v[104:107], v[80:95]
	ds_read_b128 v[234:237], v186 offset:40960
	s_waitcnt lgkmcnt(7)
	v_mfma_f32_32x32x16_bf16 v[80:95], v[238:241], v[100:103], v[80:95]
	ds_read_b128 v[238:241], v187 offset:40960
	s_waitcnt lgkmcnt(7)
	v_mfma_f32_32x32x16_bf16 v[80:95], v[242:245], v[96:99], v[80:95]
	ds_read_b128 v[242:245], v188 offset:40960
	s_waitcnt lgkmcnt(7)
	v_mfma_f32_32x32x16_bf16 v[80:95], v[214:217], v[128:131], v[80:95]
	ds_read_b128 v[214:217], v189 offset:40960
	s_waitcnt lgkmcnt(7)
	v_mfma_f32_32x32x16_bf16 v[80:95], v[218:221], v[132:135], v[80:95]
	ds_read_b128 v[218:221], v190 offset:40960
	s_waitcnt lgkmcnt(7)
	v_mfma_f32_32x32x16_bf16 v[80:95], v[222:225], v[136:139], v[80:95]
	ds_read_b128 v[222:225], v191 offset:40960
	s_waitcnt lgkmcnt(7)
	v_mfma_f32_32x32x16_bf16 v[80:95], v[226:229], v[140:143], v[80:95]
	ds_read_b128 v[226:229], v192 offset:40960
	s_waitcnt lgkmcnt(7)
	v_mfma_f32_32x32x16_bf16 v[64:79], v[230:233], v[124:127], 0
	ds_read_b128 v[230:233], v203 offset:53248
	s_waitcnt lgkmcnt(7)
	v_mfma_f32_32x32x16_bf16 v[64:79], v[234:237], v[120:123], v[64:79]
	ds_read_b128 v[234:237], v204 offset:53248
	s_waitcnt lgkmcnt(7)
	v_mfma_f32_32x32x16_bf16 v[64:79], v[238:241], v[116:119], v[64:79]
	ds_read_b128 v[238:241], v205 offset:53248
	s_waitcnt lgkmcnt(7)
	v_mfma_f32_32x32x16_bf16 v[64:79], v[242:245], v[112:115], v[64:79]
	ds_read_b128 v[242:245], v206 offset:53248
	s_waitcnt lgkmcnt(7)
	v_mfma_f32_32x32x16_bf16 v[64:79], v[214:217], v[108:111], v[64:79]
	s_waitcnt lgkmcnt(6)
	v_mfma_f32_32x32x16_bf16 v[64:79], v[218:221], v[104:107], v[64:79]
	s_waitcnt lgkmcnt(5)
	v_mfma_f32_32x32x16_bf16 v[64:79], v[222:225], v[100:103], v[64:79]
	ds_read_b64_tr_b16 v[214:215], v184
	ds_read_b64_tr_b16 v[216:217], v184 offset:2048
	s_waitcnt lgkmcnt(6)
	v_mfma_f32_32x32x16_bf16 v[64:79], v[226:229], v[96:99], v[64:79]
	ds_read_b64_tr_b16 v[218:219], v184 offset:4096
	ds_read_b64_tr_b16 v[220:221], v184 offset:6144
	s_waitcnt lgkmcnt(7)
	v_mfma_f32_32x32x16_bf16 v[64:79], v[230:233], v[128:131], v[64:79]
	ds_read_b64_tr_b16 v[222:223], v184 offset:8192
	ds_read_b64_tr_b16 v[224:225], v184 offset:10240
	s_waitcnt lgkmcnt(8)
	v_mfma_f32_32x32x16_bf16 v[64:79], v[234:237], v[132:135], v[64:79]
	ds_read_b64_tr_b16 v[226:227], v184 offset:12288
	ds_read_b64_tr_b16 v[228:229], v184 offset:14336
	s_waitcnt lgkmcnt(9)
	v_mfma_f32_32x32x16_bf16 v[64:79], v[238:241], v[136:139], v[64:79]
	ds_read_b64_tr_b16 v[230:231], v184 offset:512
	ds_read_b64_tr_b16 v[232:233], v184 offset:2560
	s_waitcnt lgkmcnt(10)
	v_mfma_f32_32x32x16_bf16 v[64:79], v[242:245], v[140:143], v[64:79]
	ds_read_b64_tr_b16 v[234:235], v184 offset:4608
	ds_read_b64_tr_b16 v[236:237], v184 offset:6656
	s_waitcnt lgkmcnt(10)
	v_mfma_f32_32x32x16_bf16 v[0:15], v[144:147], v[214:217], v[0:15]
	ds_read_b64_tr_b16 v[238:239], v184 offset:8704
	ds_read_b64_tr_b16 v[240:241], v184 offset:10752
	s_waitcnt lgkmcnt(10)
	v_mfma_f32_32x32x16_bf16 v[0:15], v[148:151], v[218:221], v[0:15]
	ds_read_b64_tr_b16 v[242:243], v184 offset:12800
	ds_read_b64_tr_b16 v[244:245], v184 offset:14848
	s_waitcnt lgkmcnt(10)
	v_mfma_f32_32x32x16_bf16 v[0:15], v[152:155], v[222:225], v[0:15]
	ds_read_b64_tr_b16 v[214:215], v184 offset:1024
	ds_read_b64_tr_b16 v[216:217], v184 offset:3072
	s_waitcnt lgkmcnt(10)
	v_mfma_f32_32x32x16_bf16 v[0:15], v[156:159], v[226:229], v[0:15]
	ds_read_b64_tr_b16 v[218:219], v184 offset:5120
	ds_read_b64_tr_b16 v[220:221], v184 offset:7168
	s_waitcnt lgkmcnt(10)
	v_mfma_f32_32x32x16_bf16 v[48:63], v[144:147], v[230:233], v[48:63]
	ds_read_b64_tr_b16 v[222:223], v184 offset:9216
	ds_read_b64_tr_b16 v[224:225], v184 offset:11264
	s_waitcnt lgkmcnt(10)
	v_mfma_f32_32x32x16_bf16 v[48:63], v[148:151], v[234:237], v[48:63]
	ds_read_b64_tr_b16 v[226:227], v184 offset:13312
	ds_read_b64_tr_b16 v[228:229], v184 offset:15360
	s_waitcnt lgkmcnt(10)
	v_mfma_f32_32x32x16_bf16 v[48:63], v[152:155], v[238:241], v[48:63]
	ds_read_b64_tr_b16 v[230:231], v184 offset:1536
	ds_read_b64_tr_b16 v[232:233], v184 offset:3584
	s_waitcnt lgkmcnt(10)
	v_mfma_f32_32x32x16_bf16 v[48:63], v[156:159], v[242:245], v[48:63]
	ds_read_b64_tr_b16 v[234:235], v184 offset:5632
	ds_read_b64_tr_b16 v[236:237], v184 offset:7680
	s_waitcnt lgkmcnt(10)
	v_mfma_f32_32x32x16_bf16 v[32:47], v[144:147], v[214:217], v[32:47]
	ds_read_b64_tr_b16 v[238:239], v184 offset:9728
	ds_read_b64_tr_b16 v[240:241], v184 offset:11776
	s_waitcnt lgkmcnt(10)
	v_mfma_f32_32x32x16_bf16 v[32:47], v[148:151], v[218:221], v[32:47]
	ds_read_b64_tr_b16 v[242:243], v184 offset:13824
	ds_read_b64_tr_b16 v[244:245], v184 offset:15872
	s_waitcnt lgkmcnt(10)
	v_mfma_f32_32x32x16_bf16 v[32:47], v[152:155], v[222:225], v[32:47]
	s_waitcnt lgkmcnt(8)
	v_mfma_f32_32x32x16_bf16 v[32:47], v[156:159], v[226:229], v[32:47]
	s_waitcnt lgkmcnt(6)
	v_mfma_f32_32x32x16_bf16 v[16:31], v[144:147], v[230:233], v[16:31]
	s_waitcnt lgkmcnt(4)
	v_mfma_f32_32x32x16_bf16 v[16:31], v[148:151], v[234:237], v[16:31]
	s_waitcnt lgkmcnt(2)
	v_mfma_f32_32x32x16_bf16 v[16:31], v[152:155], v[238:241], v[16:31]
	s_waitcnt lgkmcnt(0)
	v_mfma_f32_32x32x16_bf16 v[16:31], v[156:159], v[242:245], v[16:31]
	s_add_i32 s58, s58, 1
	s_addk_i32 s51, 0x80
	s_cmp_eq_u32 s96, 1
	s_cbranch_scc0 .Lm2_cw_e
	s_waitcnt vmcnt(0)
.Lm2_cw_e:
	s_waitcnt lgkmcnt(0)
	s_barrier
	s_cmp_eq_u32 s96, 1
	s_cbranch_scc0 .Lm2_lskip_e
	s_cmp_gt_u32 s58, s19
	s_cbranch_scc1 .Lm2_iss_end_le
	s_cmp_eq_u32 s58, 2
	s_cbranch_scc1 .Lm2_iss_nov_le
	s_mov_b32 m0, s54
	v_lshl_add_u64 v[254:255], v[164:165], 1, s[100:101]
	global_load_lds_dwordx4 v[254:255], off
	s_mov_b32 m0, s55
	v_lshl_add_u64 v[254:255], v[166:167], 1, s[100:101]
	global_load_lds_dwordx4 v[254:255], off

.Lm2_lw_e:
	s_waitcnt lgkmcnt(0)
	s_barrier
	s_cmp_ge_u32 s58, s19
	s_cbranch_scc0 .Lmla_loop
	ds_read_b128 v[214:217], v193 offset:57344
	ds_read_b128 v[218:221], v186 offset:57344
	ds_read_b128 v[222:225], v187 offset:57344
	ds_read_b128 v[226:229], v188 offset:57344
	ds_read_b128 v[230:233], v189 offset:57344
	ds_read_b128 v[234:237], v190 offset:57344
	ds_read_b128 v[238:241], v191 offset:57344
	ds_read_b128 v[242:245], v192 offset:57344
	s_cmp_eq_u32 s96, 0
	s_cbranch_scc0 .Lm2_cskip_t
	s_cmp_gt_u32 s58, s19
	s_cbranch_scc1 .Lm2_iss_end_ct
	s_cmp_eq_u32 s58, 2
	s_cbranch_scc1 .Lm2_iss_nov_ct
	s_mov_b32 m0, s54
	v_lshl_add_u64 v[254:255], v[164:165], 1, s[100:101]
	global_load_lds_dwordx4 v[254:255], off
	s_mov_b32 m0, s55
	v_lshl_add_u64 v[254:255], v[166:167], 1, s[100:101]
	global_load_lds_dwordx4 v[254:255], off

.Lm2_lw_t:
	s_waitcnt lgkmcnt(0)
	s_barrier
	ds_read_b64_tr_b16 v[214:215], v184
	ds_read_b64_tr_b16 v[216:217], v184 offset:2048
	ds_read_b64_tr_b16 v[218:219], v184 offset:4096
	ds_read_b64_tr_b16 v[220:221], v184 offset:6144
	ds_read_b64_tr_b16 v[222:223], v184 offset:8192
	ds_read_b64_tr_b16 v[224:225], v184 offset:10240
	ds_read_b64_tr_b16 v[226:227], v184 offset:12288
	ds_read_b64_tr_b16 v[228:229], v184 offset:14336
	ds_read_b64_tr_b16 v[230:231], v184 offset:512
	ds_read_b64_tr_b16 v[232:233], v184 offset:2560
	ds_read_b64_tr_b16 v[234:235], v184 offset:4608
	ds_read_b64_tr_b16 v[236:237], v184 offset:6656
	s_waitcnt lgkmcnt(10)
	v_mfma_f32_32x32x16_bf16 v[0:15], v[144:147], v[214:217], v[0:15]
	ds_read_b64_tr_b16 v[238:239], v184 offset:8704
	ds_read_b64_tr_b16 v[240:241], v184 offset:10752
	s_waitcnt lgkmcnt(10)
	v_mfma_f32_32x32x16_bf16 v[0:15], v[148:151], v[218:221], v[0:15]
	ds_read_b64_tr_b16 v[242:243], v184 offset:12800
	ds_read_b64_tr_b16 v[244:245], v184 offset:14848
	s_waitcnt lgkmcnt(10)
	v_mfma_f32_32x32x16_bf16 v[0:15], v[152:155], v[222:225], v[0:15]
	ds_read_b64_tr_b16 v[214:215], v184 offset:1024
	ds_read_b64_tr_b16 v[216:217], v184 offset:3072
	s_waitcnt lgkmcnt(10)
	v_mfma_f32_32x32x16_bf16 v[0:15], v[156:159], v[226:229], v[0:15]
	ds_read_b64_tr_b16 v[218:219], v184 offset:5120
	ds_read_b64_tr_b16 v[220:221], v184 offset:7168
	s_waitcnt lgkmcnt(10)
	v_mfma_f32_32x32x16_bf16 v[48:63], v[144:147], v[230:233], v[48:63]
	ds_read_b64_tr_b16 v[222:223], v184 offset:9216
	ds_read_b64_tr_b16 v[224:225], v184 offset:11264
	s_waitcnt lgkmcnt(10)
	v_mfma_f32_32x32x16_bf16 v[48:63], v[148:151], v[234:237], v[48:63]
	ds_read_b64_tr_b16 v[226:227], v184 offset:13312
	ds_read_b64_tr_b16 v[228:229], v184 offset:15360
	s_waitcnt lgkmcnt(10)
	v_mfma_f32_32x32x16_bf16 v[48:63], v[152:155], v[238:241], v[48:63]
	ds_read_b64_tr_b16 v[230:231], v184 offset:1536
	ds_read_b64_tr_b16 v[232:233], v184 offset:3584
	s_waitcnt lgkmcnt(10)
	v_mfma_f32_32x32x16_bf16 v[48:63], v[156:159], v[242:245], v[48:63]
	ds_read_b64_tr_b16 v[234:235], v184 offset:5632
	ds_read_b64_tr_b16 v[236:237], v184 offset:7680
	s_waitcnt lgkmcnt(10)
	v_mfma_f32_32x32x16_bf16 v[32:47], v[144:147], v[214:217], v[32:47]
	ds_read_b64_tr_b16 v[238:239], v184 offset:9728
	ds_read_b64_tr_b16 v[240:241], v184 offset:11776
	s_waitcnt lgkmcnt(10)
	v_mfma_f32_32x32x16_bf16 v[32:47], v[148:151], v[218:221], v[32:47]
	ds_read_b64_tr_b16 v[242:243], v184 offset:13824
	ds_read_b64_tr_b16 v[244:245], v184 offset:15872
	s_waitcnt lgkmcnt(10)
	v_mfma_f32_32x32x16_bf16 v[32:47], v[152:155], v[222:225], v[32:47]
	s_waitcnt lgkmcnt(8)
	v_mfma_f32_32x32x16_bf16 v[32:47], v[156:159], v[226:229], v[32:47]
	s_waitcnt lgkmcnt(6)
	v_mfma_f32_32x32x16_bf16 v[16:31], v[144:147], v[230:233], v[16:31]
	s_waitcnt lgkmcnt(4)
	v_mfma_f32_32x32x16_bf16 v[16:31], v[148:151], v[234:237], v[16:31]
	s_waitcnt lgkmcnt(2)
	v_mfma_f32_32x32x16_bf16 v[16:31], v[152:155], v[238:241], v[16:31]
	s_waitcnt lgkmcnt(0)
	v_mfma_f32_32x32x16_bf16 v[16:31], v[156:159], v[242:245], v[16:31]
	s_cmp_eq_u32 s96, 0
	s_cbranch_scc0 .Lm2_f_nobar
	s_barrier
.Lm2_f_nobar:
	s_and_saveexec_b64 s[0:1], s[8:9]
	s_cbranch_execz .LBB0_550
	ds_write_b32 v182, v183
	s_branch .LBB0_550
